# removed the per-segment s_setprio flips from all three GEMM main loops
# baseline (speedup 1.0000x reference)
; #define PG8_STAGE(bufoff, gbase, voff) do { _Pragma("unroll") for (int _i = 0; _i < 2; ++_i) \
;         __builtin_amdgcn_global_load_lds((const unsigned*)((const char*)(gbase) + (voff)[_i]), (LAS unsigned*)(lds + (bufoff) + ldsw + _i * 8192), 16, 0, 0); } while (0)
; #define PG8_LDA(dst, b, h) do { _Pragma("unroll") for (int m = 0; m < 4; ++m) _Pragma("unroll") for (int k = 0; k < 2; ++k) dst[m][k] = *(const LAS bf16x8*)(lds + PG8_SA(b, h) + aoff + m * 2048 + k * 1024); } while (0)
; #define PG8_LDB(dst, b, h) do { _Pragma("unroll") for (int n = 0; n < 2; ++n) _Pragma("unroll") for (int k = 0; k < 2; ++k) dst[n][k] = *(const LAS bf16x8*)(lds + PG8_SB(b, h) + boff + n * 2048 + k * 1024); } while (0)
; #define PG8_MMA(ai, bj, At, Bt) do { __builtin_amdgcn_s_setprio(1); _Pragma("unroll") for (int m = 0; m < 4; ++m) _Pragma("unroll") for (int n = 0; n < 2; ++n) _Pragma("unroll") for (int k = 0; k < 2; ++k) \
;         acc[ai][bj][m][n] = __builtin_amdgcn_mfma_f32_16x16x32_bf16(Bt[n][k], At[m][k], acc[ai][bj][m][n], 0, 0, 0); __builtin_amdgcn_s_setprio(0); } while (0)
; #define PG8_WAIT_V(n) asm volatile("s_waitcnt vmcnt(" #n ")" ::: "memory")
; #define PG8_WAIT_L(n) asm volatile("s_waitcnt lgkmcnt(" #n ")" ::: "memory")
; #define PG8_BAR __builtin_amdgcn_s_barrier()
; #define PG8_SCHED __builtin_amdgcn_sched_barrier(0)
; template <class Epi, class Sched>
; __device__ __forceinline__ void gemm_phase(LAS unsigned char* lds, const Gemm g, const Sched& S, const Epi& E, const int tid) {
;     ...
;             PG8_LDB(B0, 0, 0); PG8_LDB(B1, 0, 1); PG8_SCHED; PG8_LDA(At, 0, 0); PG8_STAGE(PG8_SA(1, 1), a1 + hstepA, voffA);
;             PG8_WAIT_V(8); PG8_WAIT_L(0); PG8_BAR; PG8_MMA(0, 0, At, B0); PG8_MMA(0, 1, At, B1); PG8_BAR; PG8_SCHED;
;             PG8_LDA(At, 0, 1); PG8_STAGE(PG8_SB(0, 0), b2, voffB); PG8_STAGE(PG8_SB(0, 1), b2 + hstepB, voffB); PG8_STAGE(PG8_SA(0, 0), a2, voffA);
.LBB0_142:
	s_add_u32 s46, s44, 0xfff80080
	s_addc_u32 s47, s45, -1
	s_add_i32 s60, 0, 0x10000
	s_cmp_eq_u32 s59, 28
	s_cselect_b32 s49, s15, s47
	s_cselect_b32 s48, s24, s46
	s_cselect_b32 s47, s26, s58
	s_cselect_b32 s46, s39, s41
	s_add_i32 s62, 0, 0x14000
	v_add_u32_e32 v154, s60, v140
	v_add_u32_e32 v170, s62, v140
	ds_read_b128 v[142:145], v154
	ds_read_b128 v[146:149], v154 offset:1024
	ds_read_b128 v[150:153], v154 offset:2048
	ds_read_b128 v[154:157], v154 offset:3072
	ds_read_b128 v[158:161], v170
	ds_read_b128 v[162:165], v170 offset:1024
	ds_read_b128 v[166:169], v170 offset:2048
	ds_read_b128 v[170:173], v170 offset:3072
	v_lshl_add_u64 v[190:191], s[44:45], 0, v[134:135]
	s_add_i32 m0, s27, 0xc000
	ds_read_b128 v[174:177], v141
	ds_read_b128 v[178:181], v141 offset:1024
	ds_read_b128 v[182:185], v141 offset:2048
	ds_read_b128 v[186:189], v141 offset:3072
	ds_read_b128 v[202:205], v141 offset:4096
	ds_read_b128 v[206:209], v141 offset:5120
	ds_read_b128 v[210:213], v141 offset:6144
	ds_read_b128 v[214:217], v141 offset:7168
	global_load_lds_dwordx4 v[190:191], off
	v_lshl_add_u64 v[190:191], s[44:45], 0, v[136:137]
	s_add_i32 m0, s27, 0xe000
	s_nop 0
	global_load_lds_dwordx4 v[190:191], off
	s_waitcnt vmcnt(8)
	s_waitcnt lgkmcnt(0)
	s_barrier
	s_waitcnt lgkmcnt(0)
	v_mfma_f32_16x16x32_bf16 v[124:127], v[142:145], v[174:177], v[124:127]
	v_mfma_f32_16x16x32_bf16 v[120:123], v[150:153], v[174:177], v[120:123]
	v_mfma_f32_16x16x32_bf16 v[116:119], v[142:145], v[182:185], v[116:119]
	v_mfma_f32_16x16x32_bf16 v[112:115], v[150:153], v[182:185], v[112:115]
	v_mfma_f32_16x16x32_bf16 v[100:103], v[142:145], v[202:205], v[100:103]
	v_mfma_f32_16x16x32_bf16 v[96:99], v[150:153], v[202:205], v[96:99]
	v_mfma_f32_16x16x32_bf16 v[84:87], v[142:145], v[210:213], v[84:87]
	v_mfma_f32_16x16x32_bf16 v[80:83], v[150:153], v[210:213], v[80:83]
	v_mfma_f32_16x16x32_bf16 v[124:127], v[146:149], v[178:181], v[124:127]
	v_mfma_f32_16x16x32_bf16 v[120:123], v[154:157], v[178:181], v[120:123]
	v_mfma_f32_16x16x32_bf16 v[116:119], v[146:149], v[186:189], v[116:119]
	v_mfma_f32_16x16x32_bf16 v[112:115], v[154:157], v[186:189], v[112:115]
	v_mfma_f32_16x16x32_bf16 v[100:103], v[146:149], v[206:209], v[100:103]
	v_mfma_f32_16x16x32_bf16 v[96:99], v[154:157], v[206:209], v[96:99]
	v_mfma_f32_16x16x32_bf16 v[84:87], v[146:149], v[214:217], v[84:87]
	v_mfma_f32_16x16x32_bf16 v[80:83], v[154:157], v[214:217], v[80:83]
	v_mfma_f32_16x16x32_bf16 v[108:111], v[158:161], v[174:177], v[108:111]
	v_mfma_f32_16x16x32_bf16 v[104:107], v[166:169], v[174:177], v[104:107]
	v_mfma_f32_16x16x32_bf16 v[92:95], v[158:161], v[182:185], v[92:95]
	v_mfma_f32_16x16x32_bf16 v[88:91], v[166:169], v[182:185], v[88:91]
	v_mfma_f32_16x16x32_bf16 v[76:79], v[158:161], v[202:205], v[76:79]
	v_mfma_f32_16x16x32_bf16 v[72:75], v[166:169], v[202:205], v[72:75]
	v_mfma_f32_16x16x32_bf16 v[68:71], v[158:161], v[210:213], v[68:71]
	v_mfma_f32_16x16x32_bf16 v[64:67], v[166:169], v[210:213], v[64:67]
	v_mfma_f32_16x16x32_bf16 v[108:111], v[162:165], v[178:181], v[108:111]
	v_mfma_f32_16x16x32_bf16 v[104:107], v[170:173], v[178:181], v[104:107]
	v_mfma_f32_16x16x32_bf16 v[92:95], v[162:165], v[186:189], v[92:95]
	v_mfma_f32_16x16x32_bf16 v[88:91], v[170:173], v[186:189], v[88:91]
	v_mfma_f32_16x16x32_bf16 v[76:79], v[162:165], v[206:209], v[76:79]
	v_mfma_f32_16x16x32_bf16 v[72:75], v[170:173], v[206:209], v[72:75]
	v_mfma_f32_16x16x32_bf16 v[68:71], v[162:165], v[214:217], v[68:71]
	v_mfma_f32_16x16x32_bf16 v[64:67], v[170:173], v[214:217], v[64:67]
	s_barrier
	s_add_i32 s60, s60, s25
	v_lshl_add_u64 v[190:191], s[46:47], 0, v[192:193]
	s_mov_b32 m0, s60
	ds_read_b128 v[174:177], v141 offset:16384
	ds_read_b128 v[178:181], v141 offset:17408
	ds_read_b128 v[182:185], v141 offset:18432
	ds_read_b128 v[186:189], v141 offset:19456
	ds_read_b128 v[202:205], v141 offset:20480
	ds_read_b128 v[206:209], v141 offset:21504
	ds_read_b128 v[210:213], v141 offset:22528
	ds_read_b128 v[214:217], v141 offset:23552
	global_load_lds_dwordx4 v[190:191], off
	s_add_i32 m0, s60, 0x2000
	s_add_u32 s60, s46, 0x80000
	v_lshl_add_u64 v[218:219], s[46:47], 0, v[132:133]
	s_addc_u32 s61, s47, 0
	s_add_i32 s62, s62, s25
	global_load_lds_dwordx4 v[218:219], off
	v_lshl_add_u64 v[220:221], s[60:61], 0, v[192:193]
	s_mov_b32 m0, s62
	v_lshl_add_u64 v[222:223], s[48:49], 0, v[130:131]
	global_load_lds_dwordx4 v[220:221], off
	v_lshl_add_u64 v[220:221], s[60:61], 0, v[132:133]
	s_add_i32 m0, s62, 0x2000
	s_nop 0
	global_load_lds_dwordx4 v[220:221], off
	v_lshl_add_u64 v[220:221], s[48:49], 0, v[128:129]
	s_mov_b32 m0, s27
	s_nop 0
	global_load_lds_dwordx4 v[220:221], off
	s_mov_b32 m0, s28
	s_nop 0
	global_load_lds_dwordx4 v[222:223], off
	s_waitcnt vmcnt(8)
	s_waitcnt lgkmcnt(0)
	s_barrier
; #define PG8_STAGE(bufoff, gbase, voff) do { _Pragma("unroll") for (int _i = 0; _i < 2; ++_i) \
;         __builtin_amdgcn_global_load_lds((const unsigned*)((const char*)(gbase) + (voff)[_i]), (LAS unsigned*)(lds + (bufoff) + ldsw + _i * 8192), 16, 0, 0); } while (0)
; #define PG8_LDA(dst, b, h) do { _Pragma("unroll") for (int m = 0; m < 4; ++m) _Pragma("unroll") for (int k = 0; k < 2; ++k) dst[m][k] = *(const LAS bf16x8*)(lds + PG8_SA(b, h) + aoff + m * 2048 + k * 1024); } while (0)
; #define PG8_LDB(dst, b, h) do { _Pragma("unroll") for (int n = 0; n < 2; ++n) _Pragma("unroll") for (int k = 0; k < 2; ++k) dst[n][k] = *(const LAS bf16x8*)(lds + PG8_SB(b, h) + boff + n * 2048 + k * 1024); } while (0)
; #define PG8_MMA(ai, bj, At, Bt) do { __builtin_amdgcn_s_setprio(1); _Pragma("unroll") for (int m = 0; m < 4; ++m) _Pragma("unroll") for (int n = 0; n < 2; ++n) _Pragma("unroll") for (int k = 0; k < 2; ++k) \
;         acc[ai][bj][m][n] = __builtin_amdgcn_mfma_f32_16x16x32_bf16(Bt[n][k], At[m][k], acc[ai][bj][m][n], 0, 0, 0); __builtin_amdgcn_s_setprio(0); } while (0)
; #define PG8_WAIT_V(n) asm volatile("s_waitcnt vmcnt(" #n ")" ::: "memory")
; #define PG8_WAIT_L(n) asm volatile("s_waitcnt lgkmcnt(" #n ")" ::: "memory")
; #define PG8_BAR __builtin_amdgcn_s_barrier()
; #define PG8_SCHED __builtin_amdgcn_sched_barrier(0)
; template <class Epi, class Sched>
; __device__ __forceinline__ void gemm_phase(LAS unsigned char* lds, const Gemm g, const Sched& S, const Epi& E, const int tid) {
;     ...
;             PG8_WAIT_V(8); PG8_WAIT_L(0); PG8_BAR; PG8_MMA(1, 0, At, B0); PG8_MMA(1, 1, At, B1); PG8_BAR; PG8_SCHED;
;             PG8_LDB(B0, 1, 0); PG8_LDB(B1, 1, 1); PG8_SCHED; PG8_LDA(At, 1, 0); PG8_STAGE(PG8_SA(0, 1), a2 + hstepA, voffA);
;             PG8_WAIT_V(8); PG8_WAIT_L(0); PG8_BAR; PG8_MMA(0, 0, At, B0); PG8_MMA(0, 1, At, B1); PG8_BAR; PG8_SCHED;
	s_waitcnt lgkmcnt(0)
	v_mfma_f32_16x16x32_bf16 v[60:63], v[142:145], v[174:177], v[60:63]
	v_mfma_f32_16x16x32_bf16 v[56:59], v[150:153], v[174:177], v[56:59]
	v_mfma_f32_16x16x32_bf16 v[52:55], v[142:145], v[182:185], v[52:55]
	v_mfma_f32_16x16x32_bf16 v[48:51], v[150:153], v[182:185], v[48:51]
	v_mfma_f32_16x16x32_bf16 v[36:39], v[142:145], v[202:205], v[36:39]
	v_mfma_f32_16x16x32_bf16 v[32:35], v[150:153], v[202:205], v[32:35]
	v_mfma_f32_16x16x32_bf16 v[20:23], v[142:145], v[210:213], v[20:23]
	v_mfma_f32_16x16x32_bf16 v[16:19], v[150:153], v[210:213], v[16:19]
	v_mfma_f32_16x16x32_bf16 v[60:63], v[146:149], v[178:181], v[60:63]
	v_mfma_f32_16x16x32_bf16 v[56:59], v[154:157], v[178:181], v[56:59]
	v_mfma_f32_16x16x32_bf16 v[52:55], v[146:149], v[186:189], v[52:55]
	v_mfma_f32_16x16x32_bf16 v[48:51], v[154:157], v[186:189], v[48:51]
	v_mfma_f32_16x16x32_bf16 v[36:39], v[146:149], v[206:209], v[36:39]
	v_mfma_f32_16x16x32_bf16 v[32:35], v[154:157], v[206:209], v[32:35]
	v_mfma_f32_16x16x32_bf16 v[20:23], v[146:149], v[214:217], v[20:23]
	v_mfma_f32_16x16x32_bf16 v[16:19], v[154:157], v[214:217], v[16:19]
	v_mfma_f32_16x16x32_bf16 v[44:47], v[158:161], v[174:177], v[44:47]
	v_mfma_f32_16x16x32_bf16 v[40:43], v[166:169], v[174:177], v[40:43]
	v_mfma_f32_16x16x32_bf16 v[28:31], v[158:161], v[182:185], v[28:31]
	v_mfma_f32_16x16x32_bf16 v[24:27], v[166:169], v[182:185], v[24:27]
	v_mfma_f32_16x16x32_bf16 v[12:15], v[158:161], v[202:205], v[12:15]
	v_mfma_f32_16x16x32_bf16 v[8:11], v[166:169], v[202:205], v[8:11]
	v_mfma_f32_16x16x32_bf16 v[4:7], v[158:161], v[210:213], v[4:7]
	v_mfma_f32_16x16x32_bf16 v[0:3], v[166:169], v[210:213], v[0:3]
	v_mfma_f32_16x16x32_bf16 v[44:47], v[162:165], v[178:181], v[44:47]
	v_mfma_f32_16x16x32_bf16 v[40:43], v[170:173], v[178:181], v[40:43]
	v_mfma_f32_16x16x32_bf16 v[28:31], v[162:165], v[186:189], v[28:31]
	v_mfma_f32_16x16x32_bf16 v[24:27], v[170:173], v[186:189], v[24:27]
	v_mfma_f32_16x16x32_bf16 v[12:15], v[162:165], v[206:209], v[12:15]
	v_mfma_f32_16x16x32_bf16 v[8:11], v[170:173], v[206:209], v[8:11]
	v_mfma_f32_16x16x32_bf16 v[4:7], v[162:165], v[214:217], v[4:7]
	v_mfma_f32_16x16x32_bf16 v[0:3], v[170:173], v[214:217], v[0:3]
	s_barrier
	s_add_i32 s60, 0, 0x18000
	s_add_i32 s61, 0, 0x1c000
	v_add_u32_e32 v154, s60, v140
	v_add_u32_e32 v170, s61, v140
	ds_read_b128 v[142:145], v154
	ds_read_b128 v[146:149], v154 offset:1024
	ds_read_b128 v[150:153], v154 offset:2048
	ds_read_b128 v[154:157], v154 offset:3072
	ds_read_b128 v[158:161], v170
	ds_read_b128 v[162:165], v170 offset:1024
	ds_read_b128 v[166:169], v170 offset:2048
	ds_read_b128 v[170:173], v170 offset:3072
	s_add_u32 s48, s48, 0x80000
	s_addc_u32 s49, s49, 0
	s_mov_b32 m0, s50
	v_lshl_add_u64 v[234:235], s[48:49], 0, v[128:129]
	ds_read_b128 v[174:177], v141 offset:32768
	ds_read_b128 v[178:181], v141 offset:33792
	ds_read_b128 v[182:185], v141 offset:34816
	ds_read_b128 v[186:189], v141 offset:35840
	ds_read_b128 v[202:205], v141 offset:36864
	ds_read_b128 v[206:209], v141 offset:37888
	ds_read_b128 v[210:213], v141 offset:38912
	ds_read_b128 v[214:217], v141 offset:39936
	global_load_lds_dwordx4 v[234:235], off
	v_lshl_add_u64 v[234:235], s[48:49], 0, v[130:131]
	s_mov_b32 m0, s51
	s_nop 0
	global_load_lds_dwordx4 v[234:235], off
	s_waitcnt vmcnt(8)
	s_waitcnt lgkmcnt(0)
	s_barrier
	s_waitcnt lgkmcnt(0)
	v_mfma_f32_16x16x32_bf16 v[124:127], v[142:145], v[174:177], v[124:127]
	v_mfma_f32_16x16x32_bf16 v[120:123], v[150:153], v[174:177], v[120:123]
	v_mfma_f32_16x16x32_bf16 v[116:119], v[142:145], v[182:185], v[116:119]
	v_mfma_f32_16x16x32_bf16 v[112:115], v[150:153], v[182:185], v[112:115]
	v_mfma_f32_16x16x32_bf16 v[100:103], v[142:145], v[202:205], v[100:103]
	v_mfma_f32_16x16x32_bf16 v[96:99], v[150:153], v[202:205], v[96:99]
	v_mfma_f32_16x16x32_bf16 v[84:87], v[142:145], v[210:213], v[84:87]
	v_mfma_f32_16x16x32_bf16 v[80:83], v[150:153], v[210:213], v[80:83]
	v_mfma_f32_16x16x32_bf16 v[124:127], v[146:149], v[178:181], v[124:127]
	v_mfma_f32_16x16x32_bf16 v[120:123], v[154:157], v[178:181], v[120:123]
	v_mfma_f32_16x16x32_bf16 v[116:119], v[146:149], v[186:189], v[116:119]
	v_mfma_f32_16x16x32_bf16 v[112:115], v[154:157], v[186:189], v[112:115]
	v_mfma_f32_16x16x32_bf16 v[100:103], v[146:149], v[206:209], v[100:103]
	v_mfma_f32_16x16x32_bf16 v[96:99], v[154:157], v[206:209], v[96:99]
	v_mfma_f32_16x16x32_bf16 v[84:87], v[146:149], v[214:217], v[84:87]
	v_mfma_f32_16x16x32_bf16 v[80:83], v[154:157], v[214:217], v[80:83]
	v_mfma_f32_16x16x32_bf16 v[108:111], v[158:161], v[174:177], v[108:111]
	v_mfma_f32_16x16x32_bf16 v[104:107], v[166:169], v[174:177], v[104:107]
	v_mfma_f32_16x16x32_bf16 v[92:95], v[158:161], v[182:185], v[92:95]
	v_mfma_f32_16x16x32_bf16 v[88:91], v[166:169], v[182:185], v[88:91]
	v_mfma_f32_16x16x32_bf16 v[76:79], v[158:161], v[202:205], v[76:79]
	v_mfma_f32_16x16x32_bf16 v[72:75], v[166:169], v[202:205], v[72:75]
	v_mfma_f32_16x16x32_bf16 v[68:71], v[158:161], v[210:213], v[68:71]
	v_mfma_f32_16x16x32_bf16 v[64:67], v[166:169], v[210:213], v[64:67]
	v_mfma_f32_16x16x32_bf16 v[108:111], v[162:165], v[178:181], v[108:111]
	v_mfma_f32_16x16x32_bf16 v[104:107], v[170:173], v[178:181], v[104:107]
	v_mfma_f32_16x16x32_bf16 v[92:95], v[162:165], v[186:189], v[92:95]
	v_mfma_f32_16x16x32_bf16 v[88:91], v[170:173], v[186:189], v[88:91]
	v_mfma_f32_16x16x32_bf16 v[76:79], v[162:165], v[206:209], v[76:79]
	v_mfma_f32_16x16x32_bf16 v[72:75], v[170:173], v[206:209], v[72:75]
	v_mfma_f32_16x16x32_bf16 v[68:71], v[162:165], v[214:217], v[68:71]
	v_mfma_f32_16x16x32_bf16 v[64:67], v[170:173], v[214:217], v[64:67]
	s_barrier
; #define PG8_STAGE(bufoff, gbase, voff) do { _Pragma("unroll") for (int _i = 0; _i < 2; ++_i) \
;         __builtin_amdgcn_global_load_lds((const unsigned*)((const char*)(gbase) + (voff)[_i]), (LAS unsigned*)(lds + (bufoff) + ldsw + _i * 8192), 16, 0, 0); } while (0)
; #define PG8_LDA(dst, b, h) do { _Pragma("unroll") for (int m = 0; m < 4; ++m) _Pragma("unroll") for (int k = 0; k < 2; ++k) dst[m][k] = *(const LAS bf16x8*)(lds + PG8_SA(b, h) + aoff + m * 2048 + k * 1024); } while (0)
; #define PG8_MMA(ai, bj, At, Bt) do { __builtin_amdgcn_s_setprio(1); _Pragma("unroll") for (int m = 0; m < 4; ++m) _Pragma("unroll") for (int n = 0; n < 2; ++n) _Pragma("unroll") for (int k = 0; k < 2; ++k) \
;         acc[ai][bj][m][n] = __builtin_amdgcn_mfma_f32_16x16x32_bf16(Bt[n][k], At[m][k], acc[ai][bj][m][n], 0, 0, 0); __builtin_amdgcn_s_setprio(0); } while (0)
; #define PG8_WAIT_V(n) asm volatile("s_waitcnt vmcnt(" #n ")" ::: "memory")
; #define PG8_WAIT_L(n) asm volatile("s_waitcnt lgkmcnt(" #n ")" ::: "memory")
; #define PG8_BAR __builtin_amdgcn_s_barrier()
; #define PG8_SCHED __builtin_amdgcn_sched_barrier(0)
; template <class Epi, class Sched>
; __device__ __forceinline__ void gemm_phase(LAS unsigned char* lds, const Gemm g, const Sched& S, const Epi& E, const int tid) {
;     ...
;             PG8_LDA(At, 1, 1); PG8_STAGE(PG8_SB(1, 0), b3, voffB); PG8_STAGE(PG8_SB(1, 1), b3 + hstepB, voffB); PG8_STAGE(PG8_SA(1, 0), a3, voffA);
;             PG8_WAIT_V(8); PG8_WAIT_L(0); PG8_BAR; PG8_MMA(1, 0, At, B0); PG8_MMA(1, 1, At, B1); PG8_BAR; PG8_SCHED;
;         }
	s_add_i32 s48, s60, s25
	v_lshl_add_u64 v[190:191], v[190:191], 0, s[34:35]
	s_mov_b32 m0, s48
	ds_read_b128 v[174:177], v141 offset:49152
	ds_read_b128 v[178:181], v141 offset:50176
	ds_read_b128 v[182:185], v141 offset:51200
	ds_read_b128 v[186:189], v141 offset:52224
	ds_read_b128 v[202:205], v141 offset:53248
	ds_read_b128 v[206:209], v141 offset:54272
	ds_read_b128 v[210:213], v141 offset:55296
	ds_read_b128 v[214:217], v141 offset:56320
	global_load_lds_dwordx4 v[190:191], off
	s_add_i32 m0, s48, 0x2000
	s_add_u32 s46, s46, 0x80080
	v_lshl_add_u64 v[190:191], v[218:219], 0, s[34:35]
	s_addc_u32 s47, s47, 0
	s_add_i32 s48, s61, s25
	global_load_lds_dwordx4 v[190:191], off
	v_lshl_add_u64 v[190:191], s[46:47], 0, v[192:193]
	s_mov_b32 m0, s48
	s_nop 0
	global_load_lds_dwordx4 v[190:191], off
	v_lshl_add_u64 v[190:191], s[46:47], 0, v[132:133]
	s_add_i32 m0, s48, 0x2000
	s_nop 0
	global_load_lds_dwordx4 v[190:191], off
	v_lshl_add_u64 v[190:191], v[220:221], 0, s[34:35]
	s_mov_b32 m0, s54
	s_nop 0
	global_load_lds_dwordx4 v[190:191], off
	v_lshl_add_u64 v[190:191], v[222:223], 0, s[34:35]
	s_mov_b32 m0, s55
	s_nop 0
	global_load_lds_dwordx4 v[190:191], off
	s_waitcnt vmcnt(8)
	s_waitcnt lgkmcnt(0)
	s_barrier
	s_waitcnt lgkmcnt(0)
	v_mfma_f32_16x16x32_bf16 v[60:63], v[142:145], v[174:177], v[60:63]
	v_mfma_f32_16x16x32_bf16 v[56:59], v[150:153], v[174:177], v[56:59]
	v_mfma_f32_16x16x32_bf16 v[52:55], v[142:145], v[182:185], v[52:55]
	v_mfma_f32_16x16x32_bf16 v[48:51], v[150:153], v[182:185], v[48:51]
	v_mfma_f32_16x16x32_bf16 v[36:39], v[142:145], v[202:205], v[36:39]
	v_mfma_f32_16x16x32_bf16 v[32:35], v[150:153], v[202:205], v[32:35]
	v_mfma_f32_16x16x32_bf16 v[20:23], v[142:145], v[210:213], v[20:23]
	v_mfma_f32_16x16x32_bf16 v[16:19], v[150:153], v[210:213], v[16:19]
	v_mfma_f32_16x16x32_bf16 v[60:63], v[146:149], v[178:181], v[60:63]
	v_mfma_f32_16x16x32_bf16 v[56:59], v[154:157], v[178:181], v[56:59]
	v_mfma_f32_16x16x32_bf16 v[52:55], v[146:149], v[186:189], v[52:55]
	v_mfma_f32_16x16x32_bf16 v[48:51], v[154:157], v[186:189], v[48:51]
	v_mfma_f32_16x16x32_bf16 v[36:39], v[146:149], v[206:209], v[36:39]
	v_mfma_f32_16x16x32_bf16 v[32:35], v[154:157], v[206:209], v[32:35]
	v_mfma_f32_16x16x32_bf16 v[20:23], v[146:149], v[214:217], v[20:23]
	v_mfma_f32_16x16x32_bf16 v[16:19], v[154:157], v[214:217], v[16:19]
	v_mfma_f32_16x16x32_bf16 v[44:47], v[158:161], v[174:177], v[44:47]
	v_mfma_f32_16x16x32_bf16 v[40:43], v[166:169], v[174:177], v[40:43]
	v_mfma_f32_16x16x32_bf16 v[28:31], v[158:161], v[182:185], v[28:31]
	v_mfma_f32_16x16x32_bf16 v[24:27], v[166:169], v[182:185], v[24:27]
	v_mfma_f32_16x16x32_bf16 v[12:15], v[158:161], v[202:205], v[12:15]
	v_mfma_f32_16x16x32_bf16 v[8:11], v[166:169], v[202:205], v[8:11]
	v_mfma_f32_16x16x32_bf16 v[4:7], v[158:161], v[210:213], v[4:7]
	v_mfma_f32_16x16x32_bf16 v[0:3], v[166:169], v[210:213], v[0:3]
	v_mfma_f32_16x16x32_bf16 v[44:47], v[162:165], v[178:181], v[44:47]
	v_mfma_f32_16x16x32_bf16 v[40:43], v[170:173], v[178:181], v[40:43]
	v_mfma_f32_16x16x32_bf16 v[28:31], v[162:165], v[186:189], v[28:31]
	v_mfma_f32_16x16x32_bf16 v[24:27], v[170:173], v[186:189], v[24:27]
	v_mfma_f32_16x16x32_bf16 v[12:15], v[162:165], v[206:209], v[12:15]
	v_mfma_f32_16x16x32_bf16 v[8:11], v[170:173], v[206:209], v[8:11]
	v_mfma_f32_16x16x32_bf16 v[4:7], v[162:165], v[214:217], v[4:7]
	v_mfma_f32_16x16x32_bf16 v[0:3], v[170:173], v[214:217], v[0:3]
	s_barrier
	s_add_i32 s59, s59, 2
	s_add_u32 s44, s44, 0x100
	s_addc_u32 s45, s45, 0
	s_add_u32 s41, s41, 0x100
	s_addc_u32 s58, s58, 0
	s_cmp_gt_u32 s59, 29
	s_cbranch_scc0 .LBB0_142
	s_and_b64 vcc, exec, s[10:11]
	s_cbranch_vccz .LBB0_145
	s_barrier

; #define PG8_STAGE(bufoff, gbase, voff) do { _Pragma("unroll") for (int _i = 0; _i < 2; ++_i) \
;         __builtin_amdgcn_global_load_lds((const unsigned*)((const char*)(gbase) + (voff)[_i]), (LAS unsigned*)(lds + (bufoff) + ldsw + _i * 8192), 16, 0, 0); } while (0)
; #define PG8_LDA(dst, b, h) do { _Pragma("unroll") for (int m = 0; m < 4; ++m) _Pragma("unroll") for (int k = 0; k < 2; ++k) dst[m][k] = *(const LAS bf16x8*)(lds + PG8_SA(b, h) + aoff + m * 2048 + k * 1024); } while (0)
; #define PG8_LDB(dst, b, h) do { _Pragma("unroll") for (int n = 0; n < 2; ++n) _Pragma("unroll") for (int k = 0; k < 2; ++k) dst[n][k] = *(const LAS bf16x8*)(lds + PG8_SB(b, h) + boff + n * 2048 + k * 1024); } while (0)
; #define PG8_MMA(ai, bj, At, Bt) do { __builtin_amdgcn_s_setprio(1); _Pragma("unroll") for (int m = 0; m < 4; ++m) _Pragma("unroll") for (int n = 0; n < 2; ++n) _Pragma("unroll") for (int k = 0; k < 2; ++k) \
;         acc[ai][bj][m][n] = __builtin_amdgcn_mfma_f32_16x16x32_bf16(Bt[n][k], At[m][k], acc[ai][bj][m][n], 0, 0, 0); __builtin_amdgcn_s_setprio(0); } while (0)
; #define PG8_WAIT_V(n) asm volatile("s_waitcnt vmcnt(" #n ")" ::: "memory")
; #define PG8_WAIT_L(n) asm volatile("s_waitcnt lgkmcnt(" #n ")" ::: "memory")
; #define PG8_BAR __builtin_amdgcn_s_barrier()
; #define PG8_SCHED __builtin_amdgcn_sched_barrier(0)
; template <class Epi, class Sched>
; __device__ __forceinline__ void gemm_phase(LAS unsigned char* lds, const Gemm g, const Sched& S, const Epi& E, const int tid) {
;     ...
;             const bool last = (t == nt - 2);
;             const char* a1 = cA + (size_t)(t + 1) * kstep;
;             const char* a2 = last ? nA : cA + (size_t)(t + 2) * kstep; const char* b2 = last ? nB : cB + (size_t)(t + 2) * kstep;
;             const char* a3 = a2 + kstep; const char* b3 = b2 + kstep;
;             if constexpr (Epi::HAS_MID) { if (t == 16 || t == 32) E.mid(acc, cur, t, wr, wc, fr, fq); }
;             PG8_LDB(B0, 0, 0); PG8_LDB(B1, 0, 1); PG8_SCHED; PG8_LDA(At, 0, 0); PG8_STAGE(PG8_SA(1, 1), a1 + hstepA, voffA);
;             PG8_WAIT_V(8); PG8_WAIT_L(0); PG8_BAR; PG8_MMA(0, 0, At, B0); PG8_MMA(0, 1, At, B1); PG8_BAR; PG8_SCHED;
;             PG8_LDA(At, 0, 1); PG8_STAGE(PG8_SB(0, 0), b2, voffB); PG8_STAGE(PG8_SB(0, 1), b2 + hstepB, voffB); PG8_STAGE(PG8_SA(0, 0), a2, voffA);
.LBB0_174:
	s_add_u32 s2, s40, s42
	s_addc_u32 s3, s41, s43
	s_add_u32 s2, s2, 0x100
	s_addc_u32 s3, s3, 0
	s_add_u32 s15, s20, s42
	s_addc_u32 s23, s21, s43
	s_cmpk_eq_i32 s42, 0x1300
	s_cselect_b32 s45, s1, s3
	s_cselect_b32 s44, s0, s2
	s_cselect_b32 s3, s39, s23
	s_cselect_b32 s2, s38, s15
	s_add_i32 s15, 0, 0x10000
	s_add_i32 s23, 0, 0x14000
	v_add_u32_e32 v140, s15, v235
	v_add_u32_e32 v156, s23, v235
	ds_read_b128 v[128:131], v140
	ds_read_b128 v[132:135], v140 offset:1024
	ds_read_b128 v[136:139], v140 offset:2048
	ds_read_b128 v[140:143], v140 offset:3072
	ds_read_b128 v[144:147], v156
	ds_read_b128 v[148:151], v156 offset:1024
	ds_read_b128 v[152:155], v156 offset:2048
	ds_read_b128 v[156:159], v156 offset:3072
	v_lshl_add_u64 v[216:217], v[212:213], 0, s[42:43]
	s_add_i32 m0, s50, 0xc000
	ds_read_b128 v[160:163], v236
	ds_read_b128 v[164:167], v236 offset:1024
	ds_read_b128 v[168:171], v236 offset:2048
	ds_read_b128 v[172:175], v236 offset:3072
	ds_read_b128 v[176:179], v236 offset:4096
	ds_read_b128 v[180:183], v236 offset:5120
	ds_read_b128 v[184:187], v236 offset:6144
	ds_read_b128 v[188:191], v236 offset:7168
	global_load_lds_dwordx4 v[216:217], off
	v_lshl_add_u64 v[216:217], v[214:215], 0, s[42:43]
	s_add_i32 m0, s50, 0xe000
	s_nop 0
	global_load_lds_dwordx4 v[216:217], off
	s_waitcnt vmcnt(8)
	s_waitcnt lgkmcnt(0)
	s_barrier
	s_waitcnt lgkmcnt(0)
	v_mfma_f32_16x16x32_bf16 v[124:127], v[128:131], v[160:163], v[124:127]
	v_mfma_f32_16x16x32_bf16 v[120:123], v[136:139], v[160:163], v[120:123]
	v_mfma_f32_16x16x32_bf16 v[108:111], v[128:131], v[168:171], v[108:111]
	v_mfma_f32_16x16x32_bf16 v[104:107], v[136:139], v[168:171], v[104:107]
	v_mfma_f32_16x16x32_bf16 v[96:99], v[128:131], v[176:179], v[96:99]
	v_mfma_f32_16x16x32_bf16 v[88:91], v[136:139], v[176:179], v[88:91]
	v_mfma_f32_16x16x32_bf16 v[80:83], v[128:131], v[184:187], v[80:83]
	v_mfma_f32_16x16x32_bf16 v[72:75], v[136:139], v[184:187], v[72:75]
	v_mfma_f32_16x16x32_bf16 v[124:127], v[132:135], v[164:167], v[124:127]
	v_mfma_f32_16x16x32_bf16 v[120:123], v[140:143], v[164:167], v[120:123]
	v_mfma_f32_16x16x32_bf16 v[108:111], v[132:135], v[172:175], v[108:111]
	v_mfma_f32_16x16x32_bf16 v[104:107], v[140:143], v[172:175], v[104:107]
	v_mfma_f32_16x16x32_bf16 v[96:99], v[132:135], v[180:183], v[96:99]
	v_mfma_f32_16x16x32_bf16 v[88:91], v[140:143], v[180:183], v[88:91]
	v_mfma_f32_16x16x32_bf16 v[80:83], v[132:135], v[188:191], v[80:83]
	v_mfma_f32_16x16x32_bf16 v[72:75], v[140:143], v[188:191], v[72:75]
	v_mfma_f32_16x16x32_bf16 v[116:119], v[144:147], v[160:163], v[116:119]
	v_mfma_f32_16x16x32_bf16 v[112:115], v[152:155], v[160:163], v[112:115]
	v_mfma_f32_16x16x32_bf16 v[100:103], v[144:147], v[168:171], v[100:103]
	v_mfma_f32_16x16x32_bf16 v[92:95], v[152:155], v[168:171], v[92:95]
	v_mfma_f32_16x16x32_bf16 v[84:87], v[144:147], v[176:179], v[84:87]
	v_mfma_f32_16x16x32_bf16 v[76:79], v[152:155], v[176:179], v[76:79]
	v_mfma_f32_16x16x32_bf16 v[68:71], v[144:147], v[184:187], v[68:71]
	v_mfma_f32_16x16x32_bf16 v[64:67], v[152:155], v[184:187], v[64:67]
	v_mfma_f32_16x16x32_bf16 v[116:119], v[148:151], v[164:167], v[116:119]
	v_mfma_f32_16x16x32_bf16 v[112:115], v[156:159], v[164:167], v[112:115]
	v_mfma_f32_16x16x32_bf16 v[100:103], v[148:151], v[172:175], v[100:103]
	v_mfma_f32_16x16x32_bf16 v[92:95], v[156:159], v[172:175], v[92:95]
	v_mfma_f32_16x16x32_bf16 v[84:87], v[148:151], v[180:183], v[84:87]
	v_mfma_f32_16x16x32_bf16 v[76:79], v[156:159], v[180:183], v[76:79]
	v_mfma_f32_16x16x32_bf16 v[68:71], v[148:151], v[188:191], v[68:71]
	v_mfma_f32_16x16x32_bf16 v[64:67], v[156:159], v[188:191], v[64:67]
	s_barrier
	s_add_i32 s15, s15, s49
	v_lshl_add_u64 v[216:217], s[2:3], 0, v[192:193]
	s_mov_b32 m0, s15
	ds_read_b128 v[160:163], v236 offset:16384
	ds_read_b128 v[164:167], v236 offset:17408
	ds_read_b128 v[168:171], v236 offset:18432
	ds_read_b128 v[172:175], v236 offset:19456
	ds_read_b128 v[176:179], v236 offset:20480
	ds_read_b128 v[180:183], v236 offset:21504
	ds_read_b128 v[184:187], v236 offset:22528
	ds_read_b128 v[188:191], v236 offset:23552
	global_load_lds_dwordx4 v[216:217], off
	s_add_i32 m0, s15, 0x2000
	s_add_u32 s66, s2, 0xa0000
	v_lshl_add_u64 v[218:219], s[2:3], 0, v[206:207]
	s_addc_u32 s67, s3, 0
	s_add_i32 s15, s23, s49
	global_load_lds_dwordx4 v[218:219], off
	v_lshl_add_u64 v[220:221], s[66:67], 0, v[192:193]
	s_mov_b32 m0, s15
	v_lshl_add_u64 v[222:223], s[44:45], 0, v[204:205]
	global_load_lds_dwordx4 v[220:221], off
	v_lshl_add_u64 v[220:221], s[66:67], 0, v[206:207]
	s_add_i32 m0, s15, 0x2000
	s_nop 0
	global_load_lds_dwordx4 v[220:221], off
	v_lshl_add_u64 v[220:221], s[44:45], 0, v[202:203]
	s_mov_b32 m0, s50
	s_nop 0
	global_load_lds_dwordx4 v[220:221], off
	s_mov_b32 m0, s51
	s_nop 0
	global_load_lds_dwordx4 v[222:223], off
	s_waitcnt vmcnt(8)
	s_waitcnt lgkmcnt(0)
	s_barrier
; #define PG8_STAGE(bufoff, gbase, voff) do { _Pragma("unroll") for (int _i = 0; _i < 2; ++_i) \
;         __builtin_amdgcn_global_load_lds((const unsigned*)((const char*)(gbase) + (voff)[_i]), (LAS unsigned*)(lds + (bufoff) + ldsw + _i * 8192), 16, 0, 0); } while (0)
; #define PG8_LDA(dst, b, h) do { _Pragma("unroll") for (int m = 0; m < 4; ++m) _Pragma("unroll") for (int k = 0; k < 2; ++k) dst[m][k] = *(const LAS bf16x8*)(lds + PG8_SA(b, h) + aoff + m * 2048 + k * 1024); } while (0)
; #define PG8_LDB(dst, b, h) do { _Pragma("unroll") for (int n = 0; n < 2; ++n) _Pragma("unroll") for (int k = 0; k < 2; ++k) dst[n][k] = *(const LAS bf16x8*)(lds + PG8_SB(b, h) + boff + n * 2048 + k * 1024); } while (0)
; #define PG8_MMA(ai, bj, At, Bt) do { __builtin_amdgcn_s_setprio(1); _Pragma("unroll") for (int m = 0; m < 4; ++m) _Pragma("unroll") for (int n = 0; n < 2; ++n) _Pragma("unroll") for (int k = 0; k < 2; ++k) \
;         acc[ai][bj][m][n] = __builtin_amdgcn_mfma_f32_16x16x32_bf16(Bt[n][k], At[m][k], acc[ai][bj][m][n], 0, 0, 0); __builtin_amdgcn_s_setprio(0); } while (0)
; #define PG8_WAIT_V(n) asm volatile("s_waitcnt vmcnt(" #n ")" ::: "memory")
; #define PG8_WAIT_L(n) asm volatile("s_waitcnt lgkmcnt(" #n ")" ::: "memory")
; #define PG8_BAR __builtin_amdgcn_s_barrier()
; #define PG8_SCHED __builtin_amdgcn_sched_barrier(0)
; template <class Epi, class Sched>
; __device__ __forceinline__ void gemm_phase(LAS unsigned char* lds, const Gemm g, const Sched& S, const Epi& E, const int tid) {
;     ...
;             PG8_WAIT_V(8); PG8_WAIT_L(0); PG8_BAR; PG8_MMA(1, 0, At, B0); PG8_MMA(1, 1, At, B1); PG8_BAR; PG8_SCHED;
;             PG8_LDB(B0, 1, 0); PG8_LDB(B1, 1, 1); PG8_SCHED; PG8_LDA(At, 1, 0); PG8_STAGE(PG8_SA(0, 1), a2 + hstepA, voffA);
;             PG8_WAIT_V(8); PG8_WAIT_L(0); PG8_BAR; PG8_MMA(0, 0, At, B0); PG8_MMA(0, 1, At, B1); PG8_BAR; PG8_SCHED;
	s_waitcnt lgkmcnt(0)
	v_mfma_f32_16x16x32_bf16 v[60:63], v[128:131], v[160:163], v[60:63]
	v_mfma_f32_16x16x32_bf16 v[56:59], v[136:139], v[160:163], v[56:59]
	v_mfma_f32_16x16x32_bf16 v[48:51], v[128:131], v[168:171], v[48:51]
	v_mfma_f32_16x16x32_bf16 v[40:43], v[136:139], v[168:171], v[40:43]
	v_mfma_f32_16x16x32_bf16 v[32:35], v[128:131], v[176:179], v[32:35]
	v_mfma_f32_16x16x32_bf16 v[24:27], v[136:139], v[176:179], v[24:27]
	v_mfma_f32_16x16x32_bf16 v[16:19], v[128:131], v[184:187], v[16:19]
	v_mfma_f32_16x16x32_bf16 v[8:11], v[136:139], v[184:187], v[8:11]
	v_mfma_f32_16x16x32_bf16 v[60:63], v[132:135], v[164:167], v[60:63]
	v_mfma_f32_16x16x32_bf16 v[56:59], v[140:143], v[164:167], v[56:59]
	v_mfma_f32_16x16x32_bf16 v[48:51], v[132:135], v[172:175], v[48:51]
	v_mfma_f32_16x16x32_bf16 v[40:43], v[140:143], v[172:175], v[40:43]
	v_mfma_f32_16x16x32_bf16 v[32:35], v[132:135], v[180:183], v[32:35]
	v_mfma_f32_16x16x32_bf16 v[24:27], v[140:143], v[180:183], v[24:27]
	v_mfma_f32_16x16x32_bf16 v[16:19], v[132:135], v[188:191], v[16:19]
	v_mfma_f32_16x16x32_bf16 v[8:11], v[140:143], v[188:191], v[8:11]
	v_mfma_f32_16x16x32_bf16 v[52:55], v[144:147], v[160:163], v[52:55]
	v_mfma_f32_16x16x32_bf16 v[44:47], v[152:155], v[160:163], v[44:47]
	v_mfma_f32_16x16x32_bf16 v[36:39], v[144:147], v[168:171], v[36:39]
	v_mfma_f32_16x16x32_bf16 v[28:31], v[152:155], v[168:171], v[28:31]
	v_mfma_f32_16x16x32_bf16 v[20:23], v[144:147], v[176:179], v[20:23]
	v_mfma_f32_16x16x32_bf16 v[12:15], v[152:155], v[176:179], v[12:15]
	v_mfma_f32_16x16x32_bf16 v[4:7], v[144:147], v[184:187], v[4:7]
	v_mfma_f32_16x16x32_bf16 v[0:3], v[152:155], v[184:187], v[0:3]
	v_mfma_f32_16x16x32_bf16 v[52:55], v[148:151], v[164:167], v[52:55]
	v_mfma_f32_16x16x32_bf16 v[44:47], v[156:159], v[164:167], v[44:47]
	v_mfma_f32_16x16x32_bf16 v[36:39], v[148:151], v[172:175], v[36:39]
	v_mfma_f32_16x16x32_bf16 v[28:31], v[156:159], v[172:175], v[28:31]
	v_mfma_f32_16x16x32_bf16 v[20:23], v[148:151], v[180:183], v[20:23]
	v_mfma_f32_16x16x32_bf16 v[12:15], v[156:159], v[180:183], v[12:15]
	v_mfma_f32_16x16x32_bf16 v[4:7], v[148:151], v[188:191], v[4:7]
	v_mfma_f32_16x16x32_bf16 v[0:3], v[156:159], v[188:191], v[0:3]
	s_barrier
	s_add_i32 s15, 0, 0x18000
	s_add_i32 s23, 0, 0x1c000
	v_add_u32_e32 v140, s15, v235
	v_add_u32_e32 v156, s23, v235
	ds_read_b128 v[128:131], v140
	ds_read_b128 v[132:135], v140 offset:1024
	ds_read_b128 v[136:139], v140 offset:2048
	ds_read_b128 v[140:143], v140 offset:3072
	ds_read_b128 v[144:147], v156
	ds_read_b128 v[148:151], v156 offset:1024
	ds_read_b128 v[152:155], v156 offset:2048
	ds_read_b128 v[156:159], v156 offset:3072
	s_add_u32 s44, s44, 0xa0000
	s_addc_u32 s45, s45, 0
	s_mov_b32 m0, s52
	v_lshl_add_u64 v[238:239], s[44:45], 0, v[202:203]
	ds_read_b128 v[160:163], v236 offset:32768
	ds_read_b128 v[164:167], v236 offset:33792
	ds_read_b128 v[168:171], v236 offset:34816
	ds_read_b128 v[172:175], v236 offset:35840
	ds_read_b128 v[176:179], v236 offset:36864
	ds_read_b128 v[180:183], v236 offset:37888
	ds_read_b128 v[184:187], v236 offset:38912
	ds_read_b128 v[188:191], v236 offset:39936
	global_load_lds_dwordx4 v[238:239], off
	v_lshl_add_u64 v[238:239], s[44:45], 0, v[204:205]
	s_mov_b32 m0, s53
	s_nop 0
	global_load_lds_dwordx4 v[238:239], off
	s_waitcnt vmcnt(8)
	s_waitcnt lgkmcnt(0)
	s_barrier
	s_waitcnt lgkmcnt(0)
	v_mfma_f32_16x16x32_bf16 v[124:127], v[128:131], v[160:163], v[124:127]
	v_mfma_f32_16x16x32_bf16 v[120:123], v[136:139], v[160:163], v[120:123]
	v_mfma_f32_16x16x32_bf16 v[108:111], v[128:131], v[168:171], v[108:111]
	v_mfma_f32_16x16x32_bf16 v[104:107], v[136:139], v[168:171], v[104:107]
	v_mfma_f32_16x16x32_bf16 v[96:99], v[128:131], v[176:179], v[96:99]
	v_mfma_f32_16x16x32_bf16 v[88:91], v[136:139], v[176:179], v[88:91]
	v_mfma_f32_16x16x32_bf16 v[80:83], v[128:131], v[184:187], v[80:83]
	v_mfma_f32_16x16x32_bf16 v[72:75], v[136:139], v[184:187], v[72:75]
	v_mfma_f32_16x16x32_bf16 v[124:127], v[132:135], v[164:167], v[124:127]
	v_mfma_f32_16x16x32_bf16 v[120:123], v[140:143], v[164:167], v[120:123]
	v_mfma_f32_16x16x32_bf16 v[108:111], v[132:135], v[172:175], v[108:111]
	v_mfma_f32_16x16x32_bf16 v[104:107], v[140:143], v[172:175], v[104:107]
	v_mfma_f32_16x16x32_bf16 v[96:99], v[132:135], v[180:183], v[96:99]
	v_mfma_f32_16x16x32_bf16 v[88:91], v[140:143], v[180:183], v[88:91]
	v_mfma_f32_16x16x32_bf16 v[80:83], v[132:135], v[188:191], v[80:83]
	v_mfma_f32_16x16x32_bf16 v[72:75], v[140:143], v[188:191], v[72:75]
	v_mfma_f32_16x16x32_bf16 v[116:119], v[144:147], v[160:163], v[116:119]
	v_mfma_f32_16x16x32_bf16 v[112:115], v[152:155], v[160:163], v[112:115]
	v_mfma_f32_16x16x32_bf16 v[100:103], v[144:147], v[168:171], v[100:103]
	v_mfma_f32_16x16x32_bf16 v[92:95], v[152:155], v[168:171], v[92:95]
	v_mfma_f32_16x16x32_bf16 v[84:87], v[144:147], v[176:179], v[84:87]
	v_mfma_f32_16x16x32_bf16 v[76:79], v[152:155], v[176:179], v[76:79]
	v_mfma_f32_16x16x32_bf16 v[68:71], v[144:147], v[184:187], v[68:71]
	v_mfma_f32_16x16x32_bf16 v[64:67], v[152:155], v[184:187], v[64:67]
	v_mfma_f32_16x16x32_bf16 v[116:119], v[148:151], v[164:167], v[116:119]
	v_mfma_f32_16x16x32_bf16 v[112:115], v[156:159], v[164:167], v[112:115]
	v_mfma_f32_16x16x32_bf16 v[100:103], v[148:151], v[172:175], v[100:103]
	v_mfma_f32_16x16x32_bf16 v[92:95], v[156:159], v[172:175], v[92:95]
	v_mfma_f32_16x16x32_bf16 v[84:87], v[148:151], v[180:183], v[84:87]
	v_mfma_f32_16x16x32_bf16 v[76:79], v[156:159], v[180:183], v[76:79]
	v_mfma_f32_16x16x32_bf16 v[68:71], v[148:151], v[188:191], v[68:71]
	v_mfma_f32_16x16x32_bf16 v[64:67], v[156:159], v[188:191], v[64:67]
	s_barrier
; #define PG8_STAGE(bufoff, gbase, voff) do { _Pragma("unroll") for (int _i = 0; _i < 2; ++_i) \
;         __builtin_amdgcn_global_load_lds((const unsigned*)((const char*)(gbase) + (voff)[_i]), (LAS unsigned*)(lds + (bufoff) + ldsw + _i * 8192), 16, 0, 0); } while (0)
; #define PG8_LDA(dst, b, h) do { _Pragma("unroll") for (int m = 0; m < 4; ++m) _Pragma("unroll") for (int k = 0; k < 2; ++k) dst[m][k] = *(const LAS bf16x8*)(lds + PG8_SA(b, h) + aoff + m * 2048 + k * 1024); } while (0)
; #define PG8_MMA(ai, bj, At, Bt) do { __builtin_amdgcn_s_setprio(1); _Pragma("unroll") for (int m = 0; m < 4; ++m) _Pragma("unroll") for (int n = 0; n < 2; ++n) _Pragma("unroll") for (int k = 0; k < 2; ++k) \
;         acc[ai][bj][m][n] = __builtin_amdgcn_mfma_f32_16x16x32_bf16(Bt[n][k], At[m][k], acc[ai][bj][m][n], 0, 0, 0); __builtin_amdgcn_s_setprio(0); } while (0)
; #define PG8_WAIT_V(n) asm volatile("s_waitcnt vmcnt(" #n ")" ::: "memory")
; #define PG8_WAIT_L(n) asm volatile("s_waitcnt lgkmcnt(" #n ")" ::: "memory")
; #define PG8_BAR __builtin_amdgcn_s_barrier()
; #define PG8_SCHED __builtin_amdgcn_sched_barrier(0)
; template <class Epi, class Sched>
; __device__ __forceinline__ void gemm_phase(LAS unsigned char* lds, const Gemm g, const Sched& S, const Epi& E, const int tid) {
;     ...
;             PG8_LDA(At, 1, 1); PG8_STAGE(PG8_SB(1, 0), b3, voffB); PG8_STAGE(PG8_SB(1, 1), b3 + hstepB, voffB); PG8_STAGE(PG8_SA(1, 0), a3, voffA);
;             PG8_WAIT_V(8); PG8_WAIT_L(0); PG8_BAR; PG8_MMA(1, 0, At, B0); PG8_MMA(1, 1, At, B1); PG8_BAR; PG8_SCHED;
;         }
	s_add_i32 s15, s15, s49
	v_lshl_add_u64 v[216:217], v[216:217], 0, s[34:35]
	s_mov_b32 m0, s15
	ds_read_b128 v[160:163], v236 offset:49152
	ds_read_b128 v[164:167], v236 offset:50176
	ds_read_b128 v[168:171], v236 offset:51200
	ds_read_b128 v[172:175], v236 offset:52224
	ds_read_b128 v[176:179], v236 offset:53248
	ds_read_b128 v[180:183], v236 offset:54272
	ds_read_b128 v[184:187], v236 offset:55296
	ds_read_b128 v[188:191], v236 offset:56320
	global_load_lds_dwordx4 v[216:217], off
	s_add_i32 m0, s15, 0x2000
	s_add_u32 s2, s2, 0xa0080
	v_lshl_add_u64 v[216:217], v[218:219], 0, s[34:35]
	s_addc_u32 s3, s3, 0
	s_add_i32 s15, s23, s49
	global_load_lds_dwordx4 v[216:217], off
	v_lshl_add_u64 v[216:217], s[2:3], 0, v[192:193]
	s_mov_b32 m0, s15
	s_nop 0
	global_load_lds_dwordx4 v[216:217], off
	v_lshl_add_u64 v[216:217], s[2:3], 0, v[206:207]
	s_add_i32 m0, s15, 0x2000
	s_nop 0
	global_load_lds_dwordx4 v[216:217], off
	v_lshl_add_u64 v[216:217], v[220:221], 0, s[34:35]
	s_mov_b32 m0, s56
	s_nop 0
	global_load_lds_dwordx4 v[216:217], off
	v_lshl_add_u64 v[216:217], v[222:223], 0, s[34:35]
	s_mov_b32 m0, s57
	s_nop 0
	global_load_lds_dwordx4 v[216:217], off
	s_waitcnt vmcnt(8)
	s_waitcnt lgkmcnt(0)
	s_barrier
	s_waitcnt lgkmcnt(0)
	v_mfma_f32_16x16x32_bf16 v[60:63], v[128:131], v[160:163], v[60:63]
	v_mfma_f32_16x16x32_bf16 v[56:59], v[136:139], v[160:163], v[56:59]
	v_mfma_f32_16x16x32_bf16 v[48:51], v[128:131], v[168:171], v[48:51]
	v_mfma_f32_16x16x32_bf16 v[40:43], v[136:139], v[168:171], v[40:43]
	v_mfma_f32_16x16x32_bf16 v[32:35], v[128:131], v[176:179], v[32:35]
	v_mfma_f32_16x16x32_bf16 v[24:27], v[136:139], v[176:179], v[24:27]
	v_mfma_f32_16x16x32_bf16 v[16:19], v[128:131], v[184:187], v[16:19]
	v_mfma_f32_16x16x32_bf16 v[8:11], v[136:139], v[184:187], v[8:11]
	v_mfma_f32_16x16x32_bf16 v[60:63], v[132:135], v[164:167], v[60:63]
	v_mfma_f32_16x16x32_bf16 v[56:59], v[140:143], v[164:167], v[56:59]
	v_mfma_f32_16x16x32_bf16 v[48:51], v[132:135], v[172:175], v[48:51]
	v_mfma_f32_16x16x32_bf16 v[40:43], v[140:143], v[172:175], v[40:43]
	v_mfma_f32_16x16x32_bf16 v[32:35], v[132:135], v[180:183], v[32:35]
	v_mfma_f32_16x16x32_bf16 v[24:27], v[140:143], v[180:183], v[24:27]
	v_mfma_f32_16x16x32_bf16 v[16:19], v[132:135], v[188:191], v[16:19]
	v_mfma_f32_16x16x32_bf16 v[8:11], v[140:143], v[188:191], v[8:11]
	v_mfma_f32_16x16x32_bf16 v[52:55], v[144:147], v[160:163], v[52:55]
	v_mfma_f32_16x16x32_bf16 v[44:47], v[152:155], v[160:163], v[44:47]
	v_mfma_f32_16x16x32_bf16 v[36:39], v[144:147], v[168:171], v[36:39]
	v_mfma_f32_16x16x32_bf16 v[28:31], v[152:155], v[168:171], v[28:31]
	v_mfma_f32_16x16x32_bf16 v[20:23], v[144:147], v[176:179], v[20:23]
	v_mfma_f32_16x16x32_bf16 v[12:15], v[152:155], v[176:179], v[12:15]
	v_mfma_f32_16x16x32_bf16 v[4:7], v[144:147], v[184:187], v[4:7]
	v_mfma_f32_16x16x32_bf16 v[0:3], v[152:155], v[184:187], v[0:3]
	v_mfma_f32_16x16x32_bf16 v[52:55], v[148:151], v[164:167], v[52:55]
	v_mfma_f32_16x16x32_bf16 v[44:47], v[156:159], v[164:167], v[44:47]
	v_mfma_f32_16x16x32_bf16 v[36:39], v[148:151], v[172:175], v[36:39]
	v_mfma_f32_16x16x32_bf16 v[28:31], v[156:159], v[172:175], v[28:31]
	v_mfma_f32_16x16x32_bf16 v[20:23], v[148:151], v[180:183], v[20:23]
	v_mfma_f32_16x16x32_bf16 v[12:15], v[156:159], v[180:183], v[12:15]
	v_mfma_f32_16x16x32_bf16 v[4:7], v[148:151], v[188:191], v[4:7]
	v_mfma_f32_16x16x32_bf16 v[0:3], v[156:159], v[188:191], v[0:3]
	s_barrier
	s_add_i32 s2, s22, 2
	s_add_u32 s42, s42, 0x100
	s_addc_u32 s43, s43, 0
	s_cmp_gt_u32 s22, 37
	s_mov_b32 s22, s2
	s_cbranch_scc1 .LBB0_181
